# P7 epilogue: ACT stores non-temporal (keep the L2 for the GEMM operand tiles during the up-projection)
# speedup vs baseline: 1.0079x; 1.0020x over previous
; __device__ __forceinline__ unsigned cvt_pk_bf16(float lo, float hi) { unsigned r; asm volatile("v_cvt_pk_bf16_f32 %0, %1, %2" : "=v"(r) : "v"(lo), "v"(hi)); return r; }
; __device__ __forceinline__ float dpp_ror1(float x) { return __int_as_float(__builtin_amdgcn_update_dpp(0, __float_as_int(x), 0x121, 0xf, 0xf, false)); }
; __device__ __forceinline__ float dpp_ror2(float x) { return __int_as_float(__builtin_amdgcn_update_dpp(0, __float_as_int(x), 0x122, 0xf, 0xf, false)); }
;     __device__ __forceinline__ void operator()(const f32x4 (&acc)[2][2][4][2], const Unit& u, int wr, int wc, int fr, int fq) const {
;     ...
;                 for (int m = 0; m < 4; ++m) {
;                     f32x4 cur[2], h[2];
; #pragma unroll
;                     for (int bj = 0; bj < 2; ++bj) { cur[bj] = acc[ai][bj][m][n] * rs[ai][m]; f32x4 x1, x2;
; #pragma unroll
;                         for (int e = 0; e < 4; ++e) { const float c1 = dpp_ror1(cur[bj][e]), p1 = dpp_ror1(pg[bj][e]), c2 = dpp_ror2(cur[bj][e]), p2 = dpp_ror2(pg[bj][e]);
;                             x1[e] = fr >= 1 ? c1 : p1; x2[e] = fr >= 2 ? c2 : p2; }
;                         h[bj] = bb[bj] + w0[bj] * x2 + w1[bj] * x1 + w2[bj] * cur[bj]; }
;                     if (ai == 0 && wr == 0 && m == 0 && fr < 2) {
;                         *(f32x4*)(hc0 + (size_t)(u.pm * 2 + fr) * FF2 + gcol + 4 * n) = h[0]; *(f32x4*)(hc0 + (size_t)(u.pm * 2 + fr) * FF2 + FF + gcol + 4 * n) = h[1]; }
;                     f32x4 a;
; #pragma unroll
;                     for (int e = 0; e < 4; ++e) { const float g = h[0][e]; a[e] = g * __builtin_amdgcn_rcpf(1.0f + __builtin_amdgcn_exp2f(-1.4426950408889634f * g)) * h[1][e]; }
;                     const unsigned p0 = cvt_pk_bf16(a[0], a[1]), p1 = cvt_pk_bf16(a[2], a[3]);
;                     if (n == 0) { pk_lo[ai][m][0] = p0; pk_lo[ai][m][1] = p1; }
;                     else { u32x4 w; w.x = pk_lo[ai][m][0]; w.y = pk_lo[ai][m][1]; w.z = p0; w.w = p1;
;                         *(u32x4*)(act + (size_t)(u.pm * BM + ai * HALF + wr * 64 + m * 16 + fr) * FF + gcol) = w; }
.Lp7_hr1:
	ds_read_b128 v[84:87], v217
	ds_read_b128 v[80:83], v218
	v_pk_fma_f32 v[220:221], v[136:137], v[68:69], v[140:141]
	v_pk_fma_f32 v[222:223], v[138:139], v[70:71], v[142:143]
	v_pk_fma_f32 v[224:225], v[152:153], v[64:65], v[156:157]
	v_pk_fma_f32 v[226:227], v[154:155], v[66:67], v[158:159]
	v_cndmask_b32_e64 v188, v68, v76, s[98:99]
	v_cndmask_b32_e64 v189, v69, v77, s[98:99]
	v_cndmask_b32_e64 v196, v70, v78, s[98:99]
	v_cndmask_b32_e64 v197, v71, v79, s[98:99]
	v_cndmask_b32_e64 v200, v64, v72, s[98:99]
	v_cndmask_b32_e64 v201, v65, v73, s[98:99]
	v_cndmask_b32_e64 v204, v66, v74, s[98:99]
	v_cndmask_b32_e64 v205, v67, v75, s[98:99]
	v_fmac_f32_dpp v220, v188, v132 row_ror:1 row_mask:0xf bank_mask:0xf
	v_fmac_f32_dpp v221, v189, v133 row_ror:1 row_mask:0xf bank_mask:0xf
	v_fmac_f32_dpp v222, v196, v134 row_ror:1 row_mask:0xf bank_mask:0xf
	v_fmac_f32_dpp v223, v197, v135 row_ror:1 row_mask:0xf bank_mask:0xf
	v_fmac_f32_dpp v224, v200, v148 row_ror:1 row_mask:0xf bank_mask:0xf
	v_fmac_f32_dpp v225, v201, v149 row_ror:1 row_mask:0xf bank_mask:0xf
	v_fmac_f32_dpp v226, v204, v150 row_ror:1 row_mask:0xf bank_mask:0xf
	v_fmac_f32_dpp v227, v205, v151 row_ror:1 row_mask:0xf bank_mask:0xf
	v_cndmask_b32_e64 v188, v76, v68, s[40:41]
	v_cndmask_b32_e64 v189, v77, v69, s[40:41]
	v_cndmask_b32_e64 v196, v78, v70, s[40:41]
	v_cndmask_b32_e64 v197, v79, v71, s[40:41]
	v_cndmask_b32_e64 v200, v72, v64, s[40:41]
	v_cndmask_b32_e64 v201, v73, v65, s[40:41]
	v_cndmask_b32_e64 v204, v74, v66, s[40:41]
	v_cndmask_b32_e64 v205, v75, v67, s[40:41]
	v_fmac_f32_dpp v220, v188, v128 row_ror:2 row_mask:0xf bank_mask:0xf
	v_fmac_f32_dpp v221, v189, v129 row_ror:2 row_mask:0xf bank_mask:0xf
	v_fmac_f32_dpp v222, v196, v130 row_ror:2 row_mask:0xf bank_mask:0xf
	v_fmac_f32_dpp v223, v197, v131 row_ror:2 row_mask:0xf bank_mask:0xf
	v_fmac_f32_dpp v224, v200, v144 row_ror:2 row_mask:0xf bank_mask:0xf
	v_fmac_f32_dpp v225, v201, v145 row_ror:2 row_mask:0xf bank_mask:0xf
	v_fmac_f32_dpp v226, v204, v146 row_ror:2 row_mask:0xf bank_mask:0xf
	v_fmac_f32_dpp v227, v205, v147 row_ror:2 row_mask:0xf bank_mask:0xf
	v_pk_mul_f32 v[190:191], v[220:221], s[100:101] op_sel_hi:[1,0]
	v_pk_mul_f32 v[250:251], v[222:223], s[100:101] op_sel_hi:[1,0]
	v_exp_f32_e32 v190, v190
	v_exp_f32_e32 v191, v191
	v_exp_f32_e32 v250, v250
	v_exp_f32_e32 v251, v251
	v_pk_mul_f32 v[220:221], v[220:221], v[224:225]
	v_pk_mul_f32 v[222:223], v[222:223], v[226:227]
	v_pk_add_f32 v[190:191], v[190:191], 1.0 op_sel_hi:[1,0]
	v_pk_add_f32 v[250:251], v[250:251], 1.0 op_sel_hi:[1,0]
	v_rcp_f32_e32 v190, v190
	v_rcp_f32_e32 v191, v191
	v_rcp_f32_e32 v250, v250
	v_rcp_f32_e32 v251, v251
	v_pk_mul_f32 v[220:221], v[220:221], v[190:191]
	v_pk_mul_f32 v[222:223], v[222:223], v[250:251]
	v_cvt_pk_bf16_f32 v182, v220, v221
	v_cvt_pk_bf16_f32 v183, v222, v223
	s_waitcnt vmcnt(0) lgkmcnt(0)
	v_pk_mul_f32 v[60:61], v[60:61], v[228:229] op_sel_hi:[1,0]
	v_pk_mul_f32 v[62:63], v[62:63], v[228:229] op_sel_hi:[1,0]
	v_pk_mul_f32 v[56:57], v[56:57], v[228:229] op_sel_hi:[1,0]
	v_pk_mul_f32 v[58:59], v[58:59], v[228:229] op_sel_hi:[1,0]
	v_pk_fma_f32 v[220:221], v[108:109], v[60:61], v[100:101]
	v_pk_fma_f32 v[222:223], v[110:111], v[62:63], v[102:103]
	v_pk_fma_f32 v[224:225], v[104:105], v[56:57], v[96:97]
	v_pk_fma_f32 v[226:227], v[106:107], v[58:59], v[98:99]
	v_cndmask_b32_e64 v72, v60, v92, s[98:99]
	v_cndmask_b32_e64 v73, v61, v93, s[98:99]
	v_cndmask_b32_e64 v74, v62, v94, s[98:99]
	v_cndmask_b32_e64 v75, v63, v95, s[98:99]
	v_cndmask_b32_e64 v76, v56, v88, s[98:99]
	v_cndmask_b32_e64 v77, v57, v89, s[98:99]
	v_cndmask_b32_e64 v78, v58, v90, s[98:99]
	v_cndmask_b32_e64 v79, v59, v91, s[98:99]
	v_fmac_f32_dpp v220, v72, v116 row_ror:1 row_mask:0xf bank_mask:0xf
	v_fmac_f32_dpp v221, v73, v117 row_ror:1 row_mask:0xf bank_mask:0xf
	v_fmac_f32_dpp v222, v74, v118 row_ror:1 row_mask:0xf bank_mask:0xf
	v_fmac_f32_dpp v223, v75, v119 row_ror:1 row_mask:0xf bank_mask:0xf
	v_fmac_f32_dpp v224, v76, v112 row_ror:1 row_mask:0xf bank_mask:0xf
	v_fmac_f32_dpp v225, v77, v113 row_ror:1 row_mask:0xf bank_mask:0xf
	v_fmac_f32_dpp v226, v78, v114 row_ror:1 row_mask:0xf bank_mask:0xf
	v_fmac_f32_dpp v227, v79, v115 row_ror:1 row_mask:0xf bank_mask:0xf
	v_cndmask_b32_e64 v72, v92, v60, s[40:41]
	v_cndmask_b32_e64 v73, v93, v61, s[40:41]
	v_cndmask_b32_e64 v74, v94, v62, s[40:41]
	v_cndmask_b32_e64 v75, v95, v63, s[40:41]
	v_cndmask_b32_e64 v76, v88, v56, s[40:41]
	v_cndmask_b32_e64 v77, v89, v57, s[40:41]
	v_cndmask_b32_e64 v78, v90, v58, s[40:41]
	v_cndmask_b32_e64 v79, v91, v59, s[40:41]
	v_fmac_f32_dpp v220, v72, v124 row_ror:2 row_mask:0xf bank_mask:0xf
	v_fmac_f32_dpp v221, v73, v125 row_ror:2 row_mask:0xf bank_mask:0xf
	v_fmac_f32_dpp v222, v74, v126 row_ror:2 row_mask:0xf bank_mask:0xf
	v_fmac_f32_dpp v223, v75, v127 row_ror:2 row_mask:0xf bank_mask:0xf
	v_fmac_f32_dpp v224, v76, v120 row_ror:2 row_mask:0xf bank_mask:0xf
	v_fmac_f32_dpp v225, v77, v121 row_ror:2 row_mask:0xf bank_mask:0xf
	v_fmac_f32_dpp v226, v78, v122 row_ror:2 row_mask:0xf bank_mask:0xf
	v_fmac_f32_dpp v227, v79, v123 row_ror:2 row_mask:0xf bank_mask:0xf
	s_and_saveexec_b64 s[0:1], s[12:13]
	global_store_dwordx4 v241, v[220:223], s[84:85] offset:16
	global_store_dwordx4 v249, v[224:227], s[84:85] offset:16
	s_or_b64 exec, exec, s[0:1]
	v_pk_mul_f32 v[190:191], v[220:221], s[100:101] op_sel_hi:[1,0]
	v_pk_mul_f32 v[250:251], v[222:223], s[100:101] op_sel_hi:[1,0]
	v_exp_f32_e32 v190, v190
	v_exp_f32_e32 v191, v191
	v_exp_f32_e32 v250, v250
	v_exp_f32_e32 v251, v251
	v_pk_mul_f32 v[220:221], v[220:221], v[224:225]
; __device__ __forceinline__ unsigned cvt_pk_bf16(float lo, float hi) { unsigned r; asm volatile("v_cvt_pk_bf16_f32 %0, %1, %2" : "=v"(r) : "v"(lo), "v"(hi)); return r; }
; __device__ __forceinline__ float dpp_ror1(float x) { return __int_as_float(__builtin_amdgcn_update_dpp(0, __float_as_int(x), 0x121, 0xf, 0xf, false)); }
; __device__ __forceinline__ float dpp_ror2(float x) { return __int_as_float(__builtin_amdgcn_update_dpp(0, __float_as_int(x), 0x122, 0xf, 0xf, false)); }
;     __device__ __forceinline__ void operator()(const f32x4 (&acc)[2][2][4][2], const Unit& u, int wr, int wc, int fr, int fq) const {
;     ...
;                     for (int bj = 0; bj < 2; ++bj) { cur[bj] = acc[ai][bj][m][n] * rs[ai][m]; f32x4 x1, x2;
; #pragma unroll
;                         for (int e = 0; e < 4; ++e) { const float c1 = dpp_ror1(cur[bj][e]), p1 = dpp_ror1(pg[bj][e]), c2 = dpp_ror2(cur[bj][e]), p2 = dpp_ror2(pg[bj][e]);
;                             x1[e] = fr >= 1 ? c1 : p1; x2[e] = fr >= 2 ? c2 : p2; }
;                         h[bj] = bb[bj] + w0[bj] * x2 + w1[bj] * x1 + w2[bj] * cur[bj]; }
;                     if (ai == 0 && wr == 0 && m == 0 && fr < 2) {
;                         *(f32x4*)(hc0 + (size_t)(u.pm * 2 + fr) * FF2 + gcol + 4 * n) = h[0]; *(f32x4*)(hc0 + (size_t)(u.pm * 2 + fr) * FF2 + FF + gcol + 4 * n) = h[1]; }
;                     f32x4 a;
; #pragma unroll
;                     for (int e = 0; e < 4; ++e) { const float g = h[0][e]; a[e] = g * __builtin_amdgcn_rcpf(1.0f + __builtin_amdgcn_exp2f(-1.4426950408889634f * g)) * h[1][e]; }
;                     const unsigned p0 = cvt_pk_bf16(a[0], a[1]), p1 = cvt_pk_bf16(a[2], a[3]);
;                     if (n == 0) { pk_lo[ai][m][0] = p0; pk_lo[ai][m][1] = p1; }
;                     else { u32x4 w; w.x = pk_lo[ai][m][0]; w.y = pk_lo[ai][m][1]; w.z = p0; w.w = p1;
;                         *(u32x4*)(act + (size_t)(u.pm * BM + ai * HALF + wr * 64 + m * 16 + fr) * FF + gcol) = w; }
	v_pk_mul_f32 v[222:223], v[222:223], v[226:227]
	v_pk_add_f32 v[190:191], v[190:191], 1.0 op_sel_hi:[1,0]
	v_pk_add_f32 v[250:251], v[250:251], 1.0 op_sel_hi:[1,0]
	v_rcp_f32_e32 v190, v190
	v_rcp_f32_e32 v191, v191
	v_rcp_f32_e32 v250, v250
	v_rcp_f32_e32 v251, v251
	v_pk_mul_f32 v[220:221], v[220:221], v[190:191]
	v_pk_mul_f32 v[222:223], v[222:223], v[250:251]
	v_cvt_pk_bf16_f32 v188, v220, v221
	v_cvt_pk_bf16_f32 v189, v222, v223
	global_store_dwordx4 v239, v[186:189], s[24:25] nt
	v_pk_mul_f32 v[52:53], v[52:53], v[230:231] op_sel_hi:[1,0]
	v_pk_mul_f32 v[54:55], v[54:55], v[230:231] op_sel_hi:[1,0]
	v_pk_mul_f32 v[48:49], v[48:49], v[230:231] op_sel_hi:[1,0]
	v_pk_mul_f32 v[50:51], v[50:51], v[230:231] op_sel_hi:[1,0]
	v_pk_fma_f32 v[220:221], v[108:109], v[52:53], v[100:101]
	v_pk_fma_f32 v[222:223], v[110:111], v[54:55], v[102:103]
	v_pk_fma_f32 v[224:225], v[104:105], v[48:49], v[96:97]
	v_pk_fma_f32 v[226:227], v[106:107], v[50:51], v[98:99]
	v_cndmask_b32_e64 v72, v52, v60, s[98:99]
	v_cndmask_b32_e64 v73, v53, v61, s[98:99]
	v_cndmask_b32_e64 v74, v54, v62, s[98:99]
	v_cndmask_b32_e64 v75, v55, v63, s[98:99]
	v_cndmask_b32_e64 v76, v48, v56, s[98:99]
	v_cndmask_b32_e64 v77, v49, v57, s[98:99]
	v_cndmask_b32_e64 v78, v50, v58, s[98:99]
	v_cndmask_b32_e64 v79, v51, v59, s[98:99]
	v_fmac_f32_dpp v220, v72, v116 row_ror:1 row_mask:0xf bank_mask:0xf
	v_fmac_f32_dpp v221, v73, v117 row_ror:1 row_mask:0xf bank_mask:0xf
	v_fmac_f32_dpp v222, v74, v118 row_ror:1 row_mask:0xf bank_mask:0xf
	v_fmac_f32_dpp v223, v75, v119 row_ror:1 row_mask:0xf bank_mask:0xf
	v_fmac_f32_dpp v224, v76, v112 row_ror:1 row_mask:0xf bank_mask:0xf
	v_fmac_f32_dpp v225, v77, v113 row_ror:1 row_mask:0xf bank_mask:0xf
	v_fmac_f32_dpp v226, v78, v114 row_ror:1 row_mask:0xf bank_mask:0xf
	v_fmac_f32_dpp v227, v79, v115 row_ror:1 row_mask:0xf bank_mask:0xf
	v_cndmask_b32_e64 v72, v60, v52, s[40:41]
	v_cndmask_b32_e64 v73, v61, v53, s[40:41]
	v_cndmask_b32_e64 v74, v62, v54, s[40:41]
	v_cndmask_b32_e64 v75, v63, v55, s[40:41]
	v_cndmask_b32_e64 v76, v56, v48, s[40:41]
	v_cndmask_b32_e64 v77, v57, v49, s[40:41]
	v_cndmask_b32_e64 v78, v58, v50, s[40:41]
	v_cndmask_b32_e64 v79, v59, v51, s[40:41]
	v_fmac_f32_dpp v220, v72, v124 row_ror:2 row_mask:0xf bank_mask:0xf
	v_fmac_f32_dpp v221, v73, v125 row_ror:2 row_mask:0xf bank_mask:0xf
	v_fmac_f32_dpp v222, v74, v126 row_ror:2 row_mask:0xf bank_mask:0xf
	v_fmac_f32_dpp v223, v75, v127 row_ror:2 row_mask:0xf bank_mask:0xf
	v_fmac_f32_dpp v224, v76, v120 row_ror:2 row_mask:0xf bank_mask:0xf
	v_fmac_f32_dpp v225, v77, v121 row_ror:2 row_mask:0xf bank_mask:0xf
	v_fmac_f32_dpp v226, v78, v122 row_ror:2 row_mask:0xf bank_mask:0xf
	v_fmac_f32_dpp v227, v79, v123 row_ror:2 row_mask:0xf bank_mask:0xf
	v_pk_mul_f32 v[190:191], v[220:221], s[100:101] op_sel_hi:[1,0]
	v_pk_mul_f32 v[250:251], v[222:223], s[100:101] op_sel_hi:[1,0]
	v_exp_f32_e32 v190, v190
	v_exp_f32_e32 v191, v191
	v_exp_f32_e32 v250, v250
	v_exp_f32_e32 v251, v251
	v_pk_mul_f32 v[220:221], v[220:221], v[224:225]
	v_pk_mul_f32 v[222:223], v[222:223], v[226:227]
	v_pk_add_f32 v[190:191], v[190:191], 1.0 op_sel_hi:[1,0]
	v_pk_add_f32 v[250:251], v[250:251], 1.0 op_sel_hi:[1,0]
	v_rcp_f32_e32 v190, v190
	v_rcp_f32_e32 v191, v191
	v_rcp_f32_e32 v250, v250
	v_rcp_f32_e32 v251, v251
	v_pk_mul_f32 v[220:221], v[220:221], v[190:191]
	v_pk_mul_f32 v[222:223], v[222:223], v[250:251]
	v_cvt_pk_bf16_f32 v196, v220, v221
	v_cvt_pk_bf16_f32 v197, v222, v223
	v_add_u32_e32 v243, 0x16000, v239
	global_store_dwordx4 v243, v[194:197], s[24:25] nt
	v_pk_mul_f32 v[44:45], v[44:45], v[232:233] op_sel_hi:[1,0]
	v_pk_mul_f32 v[46:47], v[46:47], v[232:233] op_sel_hi:[1,0]
	v_pk_mul_f32 v[40:41], v[40:41], v[232:233] op_sel_hi:[1,0]
	v_pk_mul_f32 v[42:43], v[42:43], v[232:233] op_sel_hi:[1,0]
	v_pk_fma_f32 v[220:221], v[108:109], v[44:45], v[100:101]
	v_pk_fma_f32 v[222:223], v[110:111], v[46:47], v[102:103]
	v_pk_fma_f32 v[224:225], v[104:105], v[40:41], v[96:97]
	v_pk_fma_f32 v[226:227], v[106:107], v[42:43], v[98:99]
	v_cndmask_b32_e64 v72, v44, v52, s[98:99]
	v_cndmask_b32_e64 v73, v45, v53, s[98:99]
	v_cndmask_b32_e64 v74, v46, v54, s[98:99]
	v_cndmask_b32_e64 v75, v47, v55, s[98:99]
	v_cndmask_b32_e64 v76, v40, v48, s[98:99]
	v_cndmask_b32_e64 v77, v41, v49, s[98:99]
	v_cndmask_b32_e64 v78, v42, v50, s[98:99]
	v_cndmask_b32_e64 v79, v43, v51, s[98:99]
	v_fmac_f32_dpp v220, v72, v116 row_ror:1 row_mask:0xf bank_mask:0xf
	v_fmac_f32_dpp v221, v73, v117 row_ror:1 row_mask:0xf bank_mask:0xf
	v_fmac_f32_dpp v222, v74, v118 row_ror:1 row_mask:0xf bank_mask:0xf
	v_fmac_f32_dpp v223, v75, v119 row_ror:1 row_mask:0xf bank_mask:0xf
	v_fmac_f32_dpp v224, v76, v112 row_ror:1 row_mask:0xf bank_mask:0xf
	v_fmac_f32_dpp v225, v77, v113 row_ror:1 row_mask:0xf bank_mask:0xf
	v_fmac_f32_dpp v226, v78, v114 row_ror:1 row_mask:0xf bank_mask:0xf
	v_fmac_f32_dpp v227, v79, v115 row_ror:1 row_mask:0xf bank_mask:0xf
	v_cndmask_b32_e64 v72, v52, v44, s[40:41]
	v_cndmask_b32_e64 v73, v53, v45, s[40:41]
	v_cndmask_b32_e64 v74, v54, v46, s[40:41]
	v_cndmask_b32_e64 v75, v55, v47, s[40:41]
	v_cndmask_b32_e64 v76, v48, v40, s[40:41]
	v_cndmask_b32_e64 v77, v49, v41, s[40:41]
	v_cndmask_b32_e64 v78, v50, v42, s[40:41]
	v_cndmask_b32_e64 v79, v51, v43, s[40:41]
	v_fmac_f32_dpp v220, v72, v124 row_ror:2 row_mask:0xf bank_mask:0xf
	v_fmac_f32_dpp v221, v73, v125 row_ror:2 row_mask:0xf bank_mask:0xf
	v_fmac_f32_dpp v222, v74, v126 row_ror:2 row_mask:0xf bank_mask:0xf
	v_fmac_f32_dpp v223, v75, v127 row_ror:2 row_mask:0xf bank_mask:0xf
	v_fmac_f32_dpp v224, v76, v120 row_ror:2 row_mask:0xf bank_mask:0xf
; __device__ __forceinline__ unsigned cvt_pk_bf16(float lo, float hi) { unsigned r; asm volatile("v_cvt_pk_bf16_f32 %0, %1, %2" : "=v"(r) : "v"(lo), "v"(hi)); return r; }
; __device__ __forceinline__ float dpp_ror1(float x) { return __int_as_float(__builtin_amdgcn_update_dpp(0, __float_as_int(x), 0x121, 0xf, 0xf, false)); }
; __device__ __forceinline__ float dpp_ror2(float x) { return __int_as_float(__builtin_amdgcn_update_dpp(0, __float_as_int(x), 0x122, 0xf, 0xf, false)); }
;     __device__ __forceinline__ void operator()(const f32x4 (&acc)[2][2][4][2], const Unit& u, int wr, int wc, int fr, int fq) const {
;     ...
;                     for (int bj = 0; bj < 2; ++bj) { cur[bj] = acc[ai][bj][m][n] * rs[ai][m]; f32x4 x1, x2;
; #pragma unroll
;                         for (int e = 0; e < 4; ++e) { const float c1 = dpp_ror1(cur[bj][e]), p1 = dpp_ror1(pg[bj][e]), c2 = dpp_ror2(cur[bj][e]), p2 = dpp_ror2(pg[bj][e]);
;                             x1[e] = fr >= 1 ? c1 : p1; x2[e] = fr >= 2 ? c2 : p2; }
;                         h[bj] = bb[bj] + w0[bj] * x2 + w1[bj] * x1 + w2[bj] * cur[bj]; }
;                     if (ai == 0 && wr == 0 && m == 0 && fr < 2) {
;                         *(f32x4*)(hc0 + (size_t)(u.pm * 2 + fr) * FF2 + gcol + 4 * n) = h[0]; *(f32x4*)(hc0 + (size_t)(u.pm * 2 + fr) * FF2 + FF + gcol + 4 * n) = h[1]; }
;                     f32x4 a;
; #pragma unroll
;                     for (int e = 0; e < 4; ++e) { const float g = h[0][e]; a[e] = g * __builtin_amdgcn_rcpf(1.0f + __builtin_amdgcn_exp2f(-1.4426950408889634f * g)) * h[1][e]; }
;                     const unsigned p0 = cvt_pk_bf16(a[0], a[1]), p1 = cvt_pk_bf16(a[2], a[3]);
;                     if (n == 0) { pk_lo[ai][m][0] = p0; pk_lo[ai][m][1] = p1; }
;                     else { u32x4 w; w.x = pk_lo[ai][m][0]; w.y = pk_lo[ai][m][1]; w.z = p0; w.w = p1;
;                         *(u32x4*)(act + (size_t)(u.pm * BM + ai * HALF + wr * 64 + m * 16 + fr) * FF + gcol) = w; }
	v_fmac_f32_dpp v225, v77, v121 row_ror:2 row_mask:0xf bank_mask:0xf
	v_fmac_f32_dpp v226, v78, v122 row_ror:2 row_mask:0xf bank_mask:0xf
	v_fmac_f32_dpp v227, v79, v123 row_ror:2 row_mask:0xf bank_mask:0xf
	v_pk_mul_f32 v[190:191], v[220:221], s[100:101] op_sel_hi:[1,0]
	v_pk_mul_f32 v[250:251], v[222:223], s[100:101] op_sel_hi:[1,0]
	v_exp_f32_e32 v190, v190
	v_exp_f32_e32 v191, v191
	v_exp_f32_e32 v250, v250
	v_exp_f32_e32 v251, v251
	v_pk_mul_f32 v[220:221], v[220:221], v[224:225]
	v_pk_mul_f32 v[222:223], v[222:223], v[226:227]
	v_pk_add_f32 v[190:191], v[190:191], 1.0 op_sel_hi:[1,0]
	v_pk_add_f32 v[250:251], v[250:251], 1.0 op_sel_hi:[1,0]
	v_rcp_f32_e32 v190, v190
	v_rcp_f32_e32 v191, v191
	v_rcp_f32_e32 v250, v250
	v_rcp_f32_e32 v251, v251
	v_pk_mul_f32 v[220:221], v[220:221], v[190:191]
	v_pk_mul_f32 v[222:223], v[222:223], v[250:251]
	v_cvt_pk_bf16_f32 v200, v220, v221
	v_cvt_pk_bf16_f32 v201, v222, v223
	v_add_u32_e32 v243, 0x2c000, v239
	global_store_dwordx4 v243, v[198:201], s[24:25] nt
	v_pk_fma_f32 v[220:221], v[108:109], v[36:37], v[100:101]
	v_pk_fma_f32 v[222:223], v[110:111], v[38:39], v[102:103]
	v_pk_fma_f32 v[224:225], v[104:105], v[32:33], v[96:97]
	v_pk_fma_f32 v[226:227], v[106:107], v[34:35], v[98:99]
	v_cndmask_b32_e64 v72, v36, v44, s[98:99]
	v_cndmask_b32_e64 v73, v37, v45, s[98:99]
	v_cndmask_b32_e64 v74, v38, v46, s[98:99]
	v_cndmask_b32_e64 v75, v39, v47, s[98:99]
	v_cndmask_b32_e64 v76, v32, v40, s[98:99]
	v_cndmask_b32_e64 v77, v33, v41, s[98:99]
	v_cndmask_b32_e64 v78, v34, v42, s[98:99]
	v_cndmask_b32_e64 v79, v35, v43, s[98:99]
	v_fmac_f32_dpp v220, v72, v116 row_ror:1 row_mask:0xf bank_mask:0xf
	v_fmac_f32_dpp v221, v73, v117 row_ror:1 row_mask:0xf bank_mask:0xf
	v_fmac_f32_dpp v222, v74, v118 row_ror:1 row_mask:0xf bank_mask:0xf
	v_fmac_f32_dpp v223, v75, v119 row_ror:1 row_mask:0xf bank_mask:0xf
	v_fmac_f32_dpp v224, v76, v112 row_ror:1 row_mask:0xf bank_mask:0xf
	v_fmac_f32_dpp v225, v77, v113 row_ror:1 row_mask:0xf bank_mask:0xf
	v_fmac_f32_dpp v226, v78, v114 row_ror:1 row_mask:0xf bank_mask:0xf
	v_fmac_f32_dpp v227, v79, v115 row_ror:1 row_mask:0xf bank_mask:0xf
	v_cndmask_b32_e64 v72, v44, v36, s[40:41]
	v_cndmask_b32_e64 v73, v45, v37, s[40:41]
	v_cndmask_b32_e64 v74, v46, v38, s[40:41]
	v_cndmask_b32_e64 v75, v47, v39, s[40:41]
	v_cndmask_b32_e64 v76, v40, v32, s[40:41]
	v_cndmask_b32_e64 v77, v41, v33, s[40:41]
	v_cndmask_b32_e64 v78, v42, v34, s[40:41]
	v_cndmask_b32_e64 v79, v43, v35, s[40:41]
	v_fmac_f32_dpp v220, v72, v124 row_ror:2 row_mask:0xf bank_mask:0xf
	v_fmac_f32_dpp v221, v73, v125 row_ror:2 row_mask:0xf bank_mask:0xf
	v_fmac_f32_dpp v222, v74, v126 row_ror:2 row_mask:0xf bank_mask:0xf
	v_fmac_f32_dpp v223, v75, v127 row_ror:2 row_mask:0xf bank_mask:0xf
	v_fmac_f32_dpp v224, v76, v120 row_ror:2 row_mask:0xf bank_mask:0xf
	v_fmac_f32_dpp v225, v77, v121 row_ror:2 row_mask:0xf bank_mask:0xf
	v_fmac_f32_dpp v226, v78, v122 row_ror:2 row_mask:0xf bank_mask:0xf
	v_fmac_f32_dpp v227, v79, v123 row_ror:2 row_mask:0xf bank_mask:0xf
	v_pk_mul_f32 v[190:191], v[220:221], s[100:101] op_sel_hi:[1,0]
	v_pk_mul_f32 v[250:251], v[222:223], s[100:101] op_sel_hi:[1,0]
	v_exp_f32_e32 v190, v190
	v_exp_f32_e32 v191, v191
	v_exp_f32_e32 v250, v250
	v_exp_f32_e32 v251, v251
	v_pk_mul_f32 v[220:221], v[220:221], v[224:225]
	v_pk_mul_f32 v[222:223], v[222:223], v[226:227]
	v_pk_add_f32 v[190:191], v[190:191], 1.0 op_sel_hi:[1,0]
	v_pk_add_f32 v[250:251], v[250:251], 1.0 op_sel_hi:[1,0]
	v_rcp_f32_e32 v190, v190
	v_rcp_f32_e32 v191, v191
	v_rcp_f32_e32 v250, v250
	v_rcp_f32_e32 v251, v251
	v_pk_mul_f32 v[220:221], v[220:221], v[190:191]
	v_pk_mul_f32 v[222:223], v[222:223], v[250:251]
	v_cvt_pk_bf16_f32 v204, v220, v221
	v_cvt_pk_bf16_f32 v205, v222, v223
	v_add_u32_e32 v243, 0x42000, v239
	global_store_dwordx4 v243, v[202:205], s[24:25] nt
	s_and_b64 vcc, exec, s[46:47]
	s_cbranch_vccz .Lp7_nopf
	s_cmp_eq_u32 s10, s71
	s_cbranch_scc1 .Lp7_nopf
	s_lshl_b32 s78, s10, 8
	s_add_i32 s78, s78, s8
	s_mov_b32 s79, 1
	v_or_b32_e32 v229, s78, v209
	v_lshlrev_b32_e32 v229, 6, v229
	v_add_u32_e32 v231, 0x2000, v229
	global_load_dwordx4 v[60:63], v229, s[26:27]
	global_load_dwordx4 v[52:55], v229, s[26:27] offset:16
	global_load_dwordx4 v[44:47], v229, s[26:27] offset:32
	global_load_dwordx4 v[36:39], v229, s[26:27] offset:48
	global_load_dwordx4 v[56:59], v231, s[26:27]
	global_load_dwordx4 v[48:51], v231, s[26:27] offset:16
	global_load_dwordx4 v[40:43], v231, s[26:27] offset:32
	global_load_dwordx4 v[32:35], v231, s[26:27] offset:48
; __device__ __forceinline__ unsigned cvt_pk_bf16(float lo, float hi) { unsigned r; asm volatile("v_cvt_pk_bf16_f32 %0, %1, %2" : "=v"(r) : "v"(lo), "v"(hi)); return r; }
; __device__ __forceinline__ float dpp_ror1(float x) { return __int_as_float(__builtin_amdgcn_update_dpp(0, __float_as_int(x), 0x121, 0xf, 0xf, false)); }
; __device__ __forceinline__ float dpp_ror2(float x) { return __int_as_float(__builtin_amdgcn_update_dpp(0, __float_as_int(x), 0x122, 0xf, 0xf, false)); }
;     __device__ __forceinline__ void operator()(const f32x4 (&acc)[2][2][4][2], const Unit& u, int wr, int wc, int fr, int fq) const {
;     ...
;                     for (int bj = 0; bj < 2; ++bj) { cur[bj] = acc[ai][bj][m][n] * rs[ai][m]; f32x4 x1, x2;
; #pragma unroll
;                         for (int e = 0; e < 4; ++e) { const float c1 = dpp_ror1(cur[bj][e]), p1 = dpp_ror1(pg[bj][e]), c2 = dpp_ror2(cur[bj][e]), p2 = dpp_ror2(pg[bj][e]);
;                             x1[e] = fr >= 1 ? c1 : p1; x2[e] = fr >= 2 ? c2 : p2; }
;                         h[bj] = bb[bj] + w0[bj] * x2 + w1[bj] * x1 + w2[bj] * cur[bj]; }
;                     if (ai == 0 && wr == 0 && m == 0 && fr < 2) {
;                         *(f32x4*)(hc0 + (size_t)(u.pm * 2 + fr) * FF2 + gcol + 4 * n) = h[0]; *(f32x4*)(hc0 + (size_t)(u.pm * 2 + fr) * FF2 + FF + gcol + 4 * n) = h[1]; }
;                     f32x4 a;
; #pragma unroll
;                     for (int e = 0; e < 4; ++e) { const float g = h[0][e]; a[e] = g * __builtin_amdgcn_rcpf(1.0f + __builtin_amdgcn_exp2f(-1.4426950408889634f * g)) * h[1][e]; }
;                     const unsigned p0 = cvt_pk_bf16(a[0], a[1]), p1 = cvt_pk_bf16(a[2], a[3]);
;                     if (n == 0) { pk_lo[ai][m][0] = p0; pk_lo[ai][m][1] = p1; }
;                     else { u32x4 w; w.x = pk_lo[ai][m][0]; w.y = pk_lo[ai][m][1]; w.z = p0; w.w = p1;
;                         *(u32x4*)(act + (size_t)(u.pm * BM + ai * HALF + wr * 64 + m * 16 + fr) * FF + gcol) = w; }
.Lp7_nopf:
	v_pk_mul_f32 v[28:29], v[28:29], v[236:237] op_sel_hi:[1,0]
	v_pk_mul_f32 v[30:31], v[30:31], v[236:237] op_sel_hi:[1,0]
	v_pk_mul_f32 v[24:25], v[24:25], v[236:237] op_sel_hi:[1,0]
	v_pk_mul_f32 v[26:27], v[26:27], v[236:237] op_sel_hi:[1,0]
	v_pk_fma_f32 v[220:221], v[108:109], v[28:29], v[100:101]
	v_pk_fma_f32 v[222:223], v[110:111], v[30:31], v[102:103]
	v_pk_fma_f32 v[224:225], v[104:105], v[24:25], v[96:97]
	v_pk_fma_f32 v[226:227], v[106:107], v[26:27], v[98:99]
	v_cndmask_b32_e64 v72, v28, v84, s[98:99]
	v_cndmask_b32_e64 v73, v29, v85, s[98:99]
	v_cndmask_b32_e64 v74, v30, v86, s[98:99]
	v_cndmask_b32_e64 v75, v31, v87, s[98:99]
	v_cndmask_b32_e64 v76, v24, v80, s[98:99]
	v_cndmask_b32_e64 v77, v25, v81, s[98:99]
	v_cndmask_b32_e64 v78, v26, v82, s[98:99]
	v_cndmask_b32_e64 v79, v27, v83, s[98:99]
	v_fmac_f32_dpp v220, v72, v116 row_ror:1 row_mask:0xf bank_mask:0xf
	v_fmac_f32_dpp v221, v73, v117 row_ror:1 row_mask:0xf bank_mask:0xf
	v_fmac_f32_dpp v222, v74, v118 row_ror:1 row_mask:0xf bank_mask:0xf
	v_fmac_f32_dpp v223, v75, v119 row_ror:1 row_mask:0xf bank_mask:0xf
	v_fmac_f32_dpp v224, v76, v112 row_ror:1 row_mask:0xf bank_mask:0xf
	v_fmac_f32_dpp v225, v77, v113 row_ror:1 row_mask:0xf bank_mask:0xf
	v_fmac_f32_dpp v226, v78, v114 row_ror:1 row_mask:0xf bank_mask:0xf
	v_fmac_f32_dpp v227, v79, v115 row_ror:1 row_mask:0xf bank_mask:0xf
	v_cndmask_b32_e64 v72, v84, v28, s[40:41]
	v_cndmask_b32_e64 v73, v85, v29, s[40:41]
	v_cndmask_b32_e64 v74, v86, v30, s[40:41]
	v_cndmask_b32_e64 v75, v87, v31, s[40:41]
	v_cndmask_b32_e64 v76, v80, v24, s[40:41]
	v_cndmask_b32_e64 v77, v81, v25, s[40:41]
	v_cndmask_b32_e64 v78, v82, v26, s[40:41]
	v_cndmask_b32_e64 v79, v83, v27, s[40:41]
	v_fmac_f32_dpp v220, v72, v124 row_ror:2 row_mask:0xf bank_mask:0xf
	v_fmac_f32_dpp v221, v73, v125 row_ror:2 row_mask:0xf bank_mask:0xf
	v_fmac_f32_dpp v222, v74, v126 row_ror:2 row_mask:0xf bank_mask:0xf
	v_fmac_f32_dpp v223, v75, v127 row_ror:2 row_mask:0xf bank_mask:0xf
	v_fmac_f32_dpp v224, v76, v120 row_ror:2 row_mask:0xf bank_mask:0xf
	v_fmac_f32_dpp v225, v77, v121 row_ror:2 row_mask:0xf bank_mask:0xf
	v_fmac_f32_dpp v226, v78, v122 row_ror:2 row_mask:0xf bank_mask:0xf
	v_fmac_f32_dpp v227, v79, v123 row_ror:2 row_mask:0xf bank_mask:0xf
	v_pk_mul_f32 v[190:191], v[220:221], s[100:101] op_sel_hi:[1,0]
	v_pk_mul_f32 v[250:251], v[222:223], s[100:101] op_sel_hi:[1,0]
	v_exp_f32_e32 v190, v190
	v_exp_f32_e32 v191, v191
	v_exp_f32_e32 v250, v250
	v_exp_f32_e32 v251, v251
	v_pk_mul_f32 v[220:221], v[220:221], v[224:225]
	v_pk_mul_f32 v[222:223], v[222:223], v[226:227]
	v_pk_add_f32 v[190:191], v[190:191], 1.0 op_sel_hi:[1,0]
	v_pk_add_f32 v[250:251], v[250:251], 1.0 op_sel_hi:[1,0]
	v_rcp_f32_e32 v190, v190
	v_rcp_f32_e32 v191, v191
	v_rcp_f32_e32 v250, v250
	v_rcp_f32_e32 v251, v251
	v_pk_mul_f32 v[220:221], v[220:221], v[190:191]
	v_pk_mul_f32 v[222:223], v[222:223], v[250:251]
	v_cvt_pk_bf16_f32 v162, v220, v221
	v_cvt_pk_bf16_f32 v163, v222, v223
	v_add_u32_e32 v243, 0xb0000, v239
	global_store_dwordx4 v243, v[160:163], s[24:25] nt
	v_pk_mul_f32 v[20:21], v[20:21], v[238:239] op_sel_hi:[1,0]
	v_pk_mul_f32 v[22:23], v[22:23], v[238:239] op_sel_hi:[1,0]
	v_pk_mul_f32 v[16:17], v[16:17], v[238:239] op_sel_hi:[1,0]
	v_pk_mul_f32 v[18:19], v[18:19], v[238:239] op_sel_hi:[1,0]
	v_pk_fma_f32 v[220:221], v[108:109], v[20:21], v[100:101]
	v_pk_fma_f32 v[222:223], v[110:111], v[22:23], v[102:103]
	v_pk_fma_f32 v[224:225], v[104:105], v[16:17], v[96:97]
	v_pk_fma_f32 v[226:227], v[106:107], v[18:19], v[98:99]
	v_cndmask_b32_e64 v72, v20, v28, s[98:99]
	v_cndmask_b32_e64 v73, v21, v29, s[98:99]
	v_cndmask_b32_e64 v74, v22, v30, s[98:99]
	v_cndmask_b32_e64 v75, v23, v31, s[98:99]
	v_cndmask_b32_e64 v76, v16, v24, s[98:99]
	v_cndmask_b32_e64 v77, v17, v25, s[98:99]
	v_cndmask_b32_e64 v78, v18, v26, s[98:99]
	v_cndmask_b32_e64 v79, v19, v27, s[98:99]
	v_fmac_f32_dpp v220, v72, v116 row_ror:1 row_mask:0xf bank_mask:0xf
	v_fmac_f32_dpp v221, v73, v117 row_ror:1 row_mask:0xf bank_mask:0xf
	v_fmac_f32_dpp v222, v74, v118 row_ror:1 row_mask:0xf bank_mask:0xf
	v_fmac_f32_dpp v223, v75, v119 row_ror:1 row_mask:0xf bank_mask:0xf
	v_fmac_f32_dpp v224, v76, v112 row_ror:1 row_mask:0xf bank_mask:0xf
	v_fmac_f32_dpp v225, v77, v113 row_ror:1 row_mask:0xf bank_mask:0xf
	v_fmac_f32_dpp v226, v78, v114 row_ror:1 row_mask:0xf bank_mask:0xf
	v_fmac_f32_dpp v227, v79, v115 row_ror:1 row_mask:0xf bank_mask:0xf
	v_cndmask_b32_e64 v72, v28, v20, s[40:41]
	v_cndmask_b32_e64 v73, v29, v21, s[40:41]
	v_cndmask_b32_e64 v74, v30, v22, s[40:41]
	v_cndmask_b32_e64 v75, v31, v23, s[40:41]
	v_cndmask_b32_e64 v76, v24, v16, s[40:41]
	v_cndmask_b32_e64 v77, v25, v17, s[40:41]
	v_cndmask_b32_e64 v78, v26, v18, s[40:41]
	v_cndmask_b32_e64 v79, v27, v19, s[40:41]
	v_fmac_f32_dpp v220, v72, v124 row_ror:2 row_mask:0xf bank_mask:0xf
	v_fmac_f32_dpp v221, v73, v125 row_ror:2 row_mask:0xf bank_mask:0xf
	v_fmac_f32_dpp v222, v74, v126 row_ror:2 row_mask:0xf bank_mask:0xf
	v_fmac_f32_dpp v223, v75, v127 row_ror:2 row_mask:0xf bank_mask:0xf
	v_fmac_f32_dpp v224, v76, v120 row_ror:2 row_mask:0xf bank_mask:0xf
	v_fmac_f32_dpp v225, v77, v121 row_ror:2 row_mask:0xf bank_mask:0xf
	v_fmac_f32_dpp v226, v78, v122 row_ror:2 row_mask:0xf bank_mask:0xf
	v_fmac_f32_dpp v227, v79, v123 row_ror:2 row_mask:0xf bank_mask:0xf
	v_pk_mul_f32 v[190:191], v[220:221], s[100:101] op_sel_hi:[1,0]
	v_pk_mul_f32 v[250:251], v[222:223], s[100:101] op_sel_hi:[1,0]
	v_exp_f32_e32 v190, v190
	v_exp_f32_e32 v191, v191
	v_exp_f32_e32 v250, v250
	v_exp_f32_e32 v251, v251
	v_pk_mul_f32 v[220:221], v[220:221], v[224:225]
; __device__ __forceinline__ unsigned cvt_pk_bf16(float lo, float hi) { unsigned r; asm volatile("v_cvt_pk_bf16_f32 %0, %1, %2" : "=v"(r) : "v"(lo), "v"(hi)); return r; }
; __device__ __forceinline__ float dpp_ror1(float x) { return __int_as_float(__builtin_amdgcn_update_dpp(0, __float_as_int(x), 0x121, 0xf, 0xf, false)); }
; __device__ __forceinline__ float dpp_ror2(float x) { return __int_as_float(__builtin_amdgcn_update_dpp(0, __float_as_int(x), 0x122, 0xf, 0xf, false)); }
;     __device__ __forceinline__ void operator()(const f32x4 (&acc)[2][2][4][2], const Unit& u, int wr, int wc, int fr, int fq) const {
;     ...
;                     for (int bj = 0; bj < 2; ++bj) { cur[bj] = acc[ai][bj][m][n] * rs[ai][m]; f32x4 x1, x2;
; #pragma unroll
;                         for (int e = 0; e < 4; ++e) { const float c1 = dpp_ror1(cur[bj][e]), p1 = dpp_ror1(pg[bj][e]), c2 = dpp_ror2(cur[bj][e]), p2 = dpp_ror2(pg[bj][e]);
;                             x1[e] = fr >= 1 ? c1 : p1; x2[e] = fr >= 2 ? c2 : p2; }
;                         h[bj] = bb[bj] + w0[bj] * x2 + w1[bj] * x1 + w2[bj] * cur[bj]; }
;                     if (ai == 0 && wr == 0 && m == 0 && fr < 2) {
;                         *(f32x4*)(hc0 + (size_t)(u.pm * 2 + fr) * FF2 + gcol + 4 * n) = h[0]; *(f32x4*)(hc0 + (size_t)(u.pm * 2 + fr) * FF2 + FF + gcol + 4 * n) = h[1]; }
;                     f32x4 a;
; #pragma unroll
;                     for (int e = 0; e < 4; ++e) { const float g = h[0][e]; a[e] = g * __builtin_amdgcn_rcpf(1.0f + __builtin_amdgcn_exp2f(-1.4426950408889634f * g)) * h[1][e]; }
;                     const unsigned p0 = cvt_pk_bf16(a[0], a[1]), p1 = cvt_pk_bf16(a[2], a[3]);
;                     if (n == 0) { pk_lo[ai][m][0] = p0; pk_lo[ai][m][1] = p1; }
;                     else { u32x4 w; w.x = pk_lo[ai][m][0]; w.y = pk_lo[ai][m][1]; w.z = p0; w.w = p1;
;                         *(u32x4*)(act + (size_t)(u.pm * BM + ai * HALF + wr * 64 + m * 16 + fr) * FF + gcol) = w; }
	v_pk_mul_f32 v[222:223], v[222:223], v[226:227]
	v_pk_add_f32 v[190:191], v[190:191], 1.0 op_sel_hi:[1,0]
	v_pk_add_f32 v[250:251], v[250:251], 1.0 op_sel_hi:[1,0]
	v_rcp_f32_e32 v190, v190
	v_rcp_f32_e32 v191, v191
	v_rcp_f32_e32 v250, v250
	v_rcp_f32_e32 v251, v251
	v_pk_mul_f32 v[220:221], v[220:221], v[190:191]
	v_pk_mul_f32 v[222:223], v[222:223], v[250:251]
	v_cvt_pk_bf16_f32 v166, v220, v221
	v_cvt_pk_bf16_f32 v167, v222, v223
	v_add_u32_e32 v243, 0xc6000, v239
	global_store_dwordx4 v243, v[164:167], s[24:25] nt
	v_pk_mul_f32 v[12:13], v[12:13], v[240:241] op_sel_hi:[1,0]
	v_pk_mul_f32 v[14:15], v[14:15], v[240:241] op_sel_hi:[1,0]
	v_pk_mul_f32 v[8:9], v[8:9], v[240:241] op_sel_hi:[1,0]
	v_pk_mul_f32 v[10:11], v[10:11], v[240:241] op_sel_hi:[1,0]
	v_pk_fma_f32 v[220:221], v[108:109], v[12:13], v[100:101]
	v_pk_fma_f32 v[222:223], v[110:111], v[14:15], v[102:103]
	v_pk_fma_f32 v[224:225], v[104:105], v[8:9], v[96:97]
	v_pk_fma_f32 v[226:227], v[106:107], v[10:11], v[98:99]
	v_cndmask_b32_e64 v72, v12, v20, s[98:99]
	v_cndmask_b32_e64 v73, v13, v21, s[98:99]
	v_cndmask_b32_e64 v74, v14, v22, s[98:99]
	v_cndmask_b32_e64 v75, v15, v23, s[98:99]
	v_cndmask_b32_e64 v76, v8, v16, s[98:99]
	v_cndmask_b32_e64 v77, v9, v17, s[98:99]
	v_cndmask_b32_e64 v78, v10, v18, s[98:99]
	v_cndmask_b32_e64 v79, v11, v19, s[98:99]
	v_fmac_f32_dpp v220, v72, v116 row_ror:1 row_mask:0xf bank_mask:0xf
	v_fmac_f32_dpp v221, v73, v117 row_ror:1 row_mask:0xf bank_mask:0xf
	v_fmac_f32_dpp v222, v74, v118 row_ror:1 row_mask:0xf bank_mask:0xf
	v_fmac_f32_dpp v223, v75, v119 row_ror:1 row_mask:0xf bank_mask:0xf
	v_fmac_f32_dpp v224, v76, v112 row_ror:1 row_mask:0xf bank_mask:0xf
	v_fmac_f32_dpp v225, v77, v113 row_ror:1 row_mask:0xf bank_mask:0xf
	v_fmac_f32_dpp v226, v78, v114 row_ror:1 row_mask:0xf bank_mask:0xf
	v_fmac_f32_dpp v227, v79, v115 row_ror:1 row_mask:0xf bank_mask:0xf
	v_cndmask_b32_e64 v72, v20, v12, s[40:41]
	v_cndmask_b32_e64 v73, v21, v13, s[40:41]
	v_cndmask_b32_e64 v74, v22, v14, s[40:41]
	v_cndmask_b32_e64 v75, v23, v15, s[40:41]
	v_cndmask_b32_e64 v76, v16, v8, s[40:41]
	v_cndmask_b32_e64 v77, v17, v9, s[40:41]
	v_cndmask_b32_e64 v78, v18, v10, s[40:41]
	v_cndmask_b32_e64 v79, v19, v11, s[40:41]
	v_fmac_f32_dpp v220, v72, v124 row_ror:2 row_mask:0xf bank_mask:0xf
	v_fmac_f32_dpp v221, v73, v125 row_ror:2 row_mask:0xf bank_mask:0xf
	v_fmac_f32_dpp v222, v74, v126 row_ror:2 row_mask:0xf bank_mask:0xf
	v_fmac_f32_dpp v223, v75, v127 row_ror:2 row_mask:0xf bank_mask:0xf
	v_fmac_f32_dpp v224, v76, v120 row_ror:2 row_mask:0xf bank_mask:0xf
	v_fmac_f32_dpp v225, v77, v121 row_ror:2 row_mask:0xf bank_mask:0xf
	v_fmac_f32_dpp v226, v78, v122 row_ror:2 row_mask:0xf bank_mask:0xf
	v_fmac_f32_dpp v227, v79, v123 row_ror:2 row_mask:0xf bank_mask:0xf
	v_pk_mul_f32 v[190:191], v[220:221], s[100:101] op_sel_hi:[1,0]
	v_pk_mul_f32 v[250:251], v[222:223], s[100:101] op_sel_hi:[1,0]
	v_exp_f32_e32 v190, v190
	v_exp_f32_e32 v191, v191
	v_exp_f32_e32 v250, v250
	v_exp_f32_e32 v251, v251
	v_pk_mul_f32 v[220:221], v[220:221], v[224:225]
	v_pk_mul_f32 v[222:223], v[222:223], v[226:227]
	v_pk_add_f32 v[190:191], v[190:191], 1.0 op_sel_hi:[1,0]
	v_pk_add_f32 v[250:251], v[250:251], 1.0 op_sel_hi:[1,0]
	v_rcp_f32_e32 v190, v190
	v_rcp_f32_e32 v191, v191
	v_rcp_f32_e32 v250, v250
	v_rcp_f32_e32 v251, v251
	v_pk_mul_f32 v[220:221], v[220:221], v[190:191]
	v_pk_mul_f32 v[222:223], v[222:223], v[250:251]
	v_cvt_pk_bf16_f32 v180, v220, v221
	v_cvt_pk_bf16_f32 v181, v222, v223
	v_add_u32_e32 v243, 0xdc000, v239
	global_store_dwordx4 v243, v[178:181], s[24:25] nt
	v_pk_fma_f32 v[220:221], v[108:109], v[4:5], v[100:101]
	v_pk_fma_f32 v[222:223], v[110:111], v[6:7], v[102:103]
	v_pk_fma_f32 v[224:225], v[104:105], v[0:1], v[96:97]
	v_pk_fma_f32 v[226:227], v[106:107], v[2:3], v[98:99]
	v_cndmask_b32_e64 v72, v4, v12, s[98:99]
	v_cndmask_b32_e64 v73, v5, v13, s[98:99]
	v_cndmask_b32_e64 v74, v6, v14, s[98:99]
	v_cndmask_b32_e64 v75, v7, v15, s[98:99]
	v_cndmask_b32_e64 v76, v0, v8, s[98:99]
	v_cndmask_b32_e64 v77, v1, v9, s[98:99]
	v_cndmask_b32_e64 v78, v2, v10, s[98:99]
	v_cndmask_b32_e64 v79, v3, v11, s[98:99]
	v_fmac_f32_dpp v220, v72, v116 row_ror:1 row_mask:0xf bank_mask:0xf
	v_fmac_f32_dpp v221, v73, v117 row_ror:1 row_mask:0xf bank_mask:0xf
	v_fmac_f32_dpp v222, v74, v118 row_ror:1 row_mask:0xf bank_mask:0xf
	v_fmac_f32_dpp v223, v75, v119 row_ror:1 row_mask:0xf bank_mask:0xf
	v_fmac_f32_dpp v224, v76, v112 row_ror:1 row_mask:0xf bank_mask:0xf
	v_fmac_f32_dpp v225, v77, v113 row_ror:1 row_mask:0xf bank_mask:0xf
	v_fmac_f32_dpp v226, v78, v114 row_ror:1 row_mask:0xf bank_mask:0xf
	v_fmac_f32_dpp v227, v79, v115 row_ror:1 row_mask:0xf bank_mask:0xf
	v_cndmask_b32_e64 v72, v12, v4, s[40:41]
	v_cndmask_b32_e64 v73, v13, v5, s[40:41]
	v_cndmask_b32_e64 v74, v14, v6, s[40:41]
	v_cndmask_b32_e64 v75, v15, v7, s[40:41]
	v_cndmask_b32_e64 v76, v8, v0, s[40:41]
	v_cndmask_b32_e64 v77, v9, v1, s[40:41]
	v_cndmask_b32_e64 v78, v10, v2, s[40:41]
	v_cndmask_b32_e64 v79, v11, v3, s[40:41]
	v_fmac_f32_dpp v220, v72, v124 row_ror:2 row_mask:0xf bank_mask:0xf
	v_fmac_f32_dpp v221, v73, v125 row_ror:2 row_mask:0xf bank_mask:0xf
	v_fmac_f32_dpp v222, v74, v126 row_ror:2 row_mask:0xf bank_mask:0xf
	v_fmac_f32_dpp v223, v75, v127 row_ror:2 row_mask:0xf bank_mask:0xf
	v_fmac_f32_dpp v224, v76, v120 row_ror:2 row_mask:0xf bank_mask:0xf
	v_fmac_f32_dpp v225, v77, v121 row_ror:2 row_mask:0xf bank_mask:0xf
	v_fmac_f32_dpp v226, v78, v122 row_ror:2 row_mask:0xf bank_mask:0xf
	v_fmac_f32_dpp v227, v79, v123 row_ror:2 row_mask:0xf bank_mask:0xf
	v_pk_mul_f32 v[190:191], v[220:221], s[100:101] op_sel_hi:[1,0]
	v_pk_mul_f32 v[250:251], v[222:223], s[100:101] op_sel_hi:[1,0]
	v_exp_f32_e32 v190, v190
	v_exp_f32_e32 v191, v191
	v_exp_f32_e32 v250, v250
	v_exp_f32_e32 v251, v251
	v_pk_mul_f32 v[220:221], v[220:221], v[224:225]
	v_pk_mul_f32 v[222:223], v[222:223], v[226:227]
	v_pk_add_f32 v[190:191], v[190:191], 1.0 op_sel_hi:[1,0]
	v_pk_add_f32 v[250:251], v[250:251], 1.0 op_sel_hi:[1,0]
	v_rcp_f32_e32 v190, v190
	v_rcp_f32_e32 v191, v191
	v_rcp_f32_e32 v250, v250
	v_rcp_f32_e32 v251, v251
	v_pk_mul_f32 v[220:221], v[220:221], v[190:191]
	v_pk_mul_f32 v[222:223], v[222:223], v[250:251]
	v_cvt_pk_bf16_f32 v184, v220, v221
	v_cvt_pk_bf16_f32 v185, v222, v223
	v_add_u32_e32 v243, 0xf2000, v239
	global_store_dwordx4 v243, v[182:185], s[24:25] nt
	s_cmp_eq_u32 s79, 0
	s_cbranch_scc1 .Lp7_nored
; __device__ __forceinline__ float row_rstd(const float* slots, int row) {
;     const f32x4* s = (const f32x4*)(slots + (size_t)row * 16);
;     const f32x4 a = s[0], b = s[1], c = s[2], d = s[3];
;     const f32x4 t = (a + b) + (c + d);
;     const float ss = (t[0] + t[1]) + (t[2] + t[3]);
;     return __builtin_amdgcn_rsqf(ss * (1.0f / 1024.0f) + 1e-6f);
; }
; __device__ __forceinline__ void load_rs(const float* slots, int rowbase, int fr, int fq, float scale, float (&rs)[2][4]) {
;     float loc[2];
; #pragma unroll
;     for (int ai = 0; ai < 2; ++ai) loc[ai] = scale * row_rstd(slots, rowbase + ai * HALF + fq * 16 + fr);
; #pragma unroll
;     for (int ai = 0; ai < 2; ++ai)
; #pragma unroll
;         for (int m = 0; m < 4; ++m) rs[ai][m] = __shfl(loc[ai], m * 16 + fr);
	s_waitcnt vmcnt(4)
	v_pk_add_f32 v[62:63], v[62:63], v[54:55]
	v_pk_add_f32 v[58:59], v[58:59], v[50:51]
	v_pk_add_f32 v[60:61], v[60:61], v[52:53]
	v_pk_add_f32 v[56:57], v[56:57], v[48:49]
	v_pk_add_f32 v[52:53], v[46:47], v[38:39]
	v_pk_add_f32 v[48:49], v[42:43], v[34:35]
	v_pk_add_f32 v[54:55], v[44:45], v[36:37]
	v_pk_add_f32 v[50:51], v[40:41], v[32:33]
	v_pk_add_f32 v[62:63], v[62:63], v[52:53]
	v_pk_add_f32 v[58:59], v[58:59], v[48:49]
	v_pk_add_f32 v[60:61], v[60:61], v[54:55]
	v_pk_add_f32 v[56:57], v[56:57], v[50:51]
	v_add_f32_e32 v60, v60, v61
	v_add_f32_e32 v56, v56, v57
	v_add_f32_e32 v61, v62, v63
	v_add_f32_e32 v57, v58, v59
	v_add_f32_e32 v60, v60, v61
	v_add_f32_e32 v56, v56, v57
	v_fmamk_f32 v60, v60, 0x3a800000, v244
	v_fmamk_f32 v56, v56, 0x3a800000, v244
	v_rsq_f32_e32 v60, v60
	v_rsq_f32_e32 v56, v56
	ds_bpermute_b32 v228, v237, v60
	ds_bpermute_b32 v230, v237, v60 offset:64
	ds_bpermute_b32 v232, v237, v60 offset:128
	ds_bpermute_b32 v234, v237, v60 offset:192
	ds_bpermute_b32 v236, v237, v56
	ds_bpermute_b32 v238, v237, v56 offset:64
	ds_bpermute_b32 v240, v237, v56 offset:128
	ds_bpermute_b32 v248, v237, v56 offset:192
	s_mov_b32 s101, s10
